# in-proj epilogue: gate bias loaded once per tile instead of per row group with vmcnt(0) each
# speedup vs baseline: 1.0051x; 1.0051x over previous
.LBB0_918:
	s_add_u32 s28, s26, 0xfffc0080
	s_addc_u32 s29, s27, -1
	s_add_i32 s48, 0, 0x10000
	v_add_u32_e32 v0, s48, v150
	ds_read_b128 v[138:141], v0
	ds_read_b128 v[142:145], v0 offset:1024
	ds_read_b128 v[146:149], v0 offset:2048
	ds_read_b128 v[152:155], v0 offset:3072
	s_cmp_eq_u32 s47, 12
	s_cselect_b32 s31, s7, s29
	s_cselect_b32 s30, s9, s28
	s_cselect_b32 s29, s19, s35
	s_cselect_b32 s28, s21, s34
	v_lshl_add_u64 v[160:161], s[26:27], 0, v[136:137]
	s_add_i32 m0, s38, 0xc000
	ds_read_b128 v[156:159], v151
	ds_read_b128 v[176:179], v151 offset:1024
	ds_read_b128 v[180:183], v151 offset:2048
	ds_read_b128 v[184:187], v151 offset:3072
	ds_read_b128 v[188:191], v151 offset:4096
	ds_read_b128 v[192:195], v151 offset:5120
	ds_read_b128 v[196:199], v151 offset:6144
	ds_read_b128 v[230:233], v151 offset:7168
	global_load_lds_dwordx4 v[160:161], off
	v_lshl_add_u64 v[160:161], s[26:27], 0, v[134:135]
	s_add_i32 m0, s38, 0xe000
	s_nop 0
	global_load_lds_dwordx4 v[160:161], off
	s_waitcnt lgkmcnt(8)
	s_barrier
	s_waitcnt lgkmcnt(0)
	s_setprio 1
	s_waitcnt lgkmcnt(0)
	v_mfma_f32_16x16x32_bf16 v[126:129], v[138:141], v[156:159], v[126:129]
	v_mfma_f32_16x16x32_bf16 v[122:125], v[146:149], v[156:159], v[122:125]
	v_mfma_f32_16x16x32_bf16 v[110:113], v[138:141], v[180:183], v[110:113]
	v_mfma_f32_16x16x32_bf16 v[106:109], v[146:149], v[180:183], v[106:109]
	v_mfma_f32_16x16x32_bf16 v[94:97], v[138:141], v[188:191], v[94:97]
	v_mfma_f32_16x16x32_bf16 v[90:93], v[146:149], v[188:191], v[90:93]
	v_mfma_f32_16x16x32_bf16 v[78:81], v[138:141], v[196:199], v[78:81]
	v_mfma_f32_16x16x32_bf16 v[74:77], v[146:149], v[196:199], v[74:77]
	v_mfma_f32_16x16x32_bf16 v[126:129], v[142:145], v[176:179], v[126:129]
	v_mfma_f32_16x16x32_bf16 v[122:125], v[152:155], v[176:179], v[122:125]
	v_mfma_f32_16x16x32_bf16 v[110:113], v[142:145], v[184:187], v[110:113]
	v_mfma_f32_16x16x32_bf16 v[106:109], v[152:155], v[184:187], v[106:109]
	v_mfma_f32_16x16x32_bf16 v[94:97], v[142:145], v[192:195], v[94:97]
	v_mfma_f32_16x16x32_bf16 v[90:93], v[152:155], v[192:195], v[90:93]
	v_mfma_f32_16x16x32_bf16 v[78:81], v[142:145], v[230:233], v[78:81]
	v_mfma_f32_16x16x32_bf16 v[74:77], v[152:155], v[230:233], v[74:77]
	s_setprio 0
	s_barrier
	s_add_i32 s50, 0, 0x14000
	s_add_i32 s48, s48, s37
	v_add_u32_e32 v0, s50, v150
	v_lshl_add_u64 v[160:161], s[28:29], 0, v[130:131]
	s_mov_b32 m0, s48
	ds_read_b128 v[234:237], v0
	ds_read_b128 v[238:241], v0 offset:1024
	ds_read_b128 v[242:245], v0 offset:2048
	ds_read_b128 v[246:249], v0 offset:3072
	global_load_lds_dwordx4 v[160:161], off
	v_lshl_add_u64 v[200:201], s[28:29], 0, v[132:133]
	s_add_i32 m0, s48, 0x2000
	s_nop 0
	global_load_lds_dwordx4 v[200:201], off
	s_barrier
	s_waitcnt lgkmcnt(0)
	s_setprio 1
	s_waitcnt lgkmcnt(0)
	v_mfma_f32_16x16x32_bf16 v[118:121], v[234:237], v[156:159], v[118:121]
	v_mfma_f32_16x16x32_bf16 v[114:117], v[242:245], v[156:159], v[114:117]
	v_mfma_f32_16x16x32_bf16 v[102:105], v[234:237], v[180:183], v[102:105]
	v_mfma_f32_16x16x32_bf16 v[98:101], v[242:245], v[180:183], v[98:101]
	v_mfma_f32_16x16x32_bf16 v[86:89], v[234:237], v[188:191], v[86:89]
	v_mfma_f32_16x16x32_bf16 v[82:85], v[242:245], v[188:191], v[82:85]
	v_mfma_f32_16x16x32_bf16 v[70:73], v[234:237], v[196:199], v[70:73]
	v_mfma_f32_16x16x32_bf16 v[66:69], v[242:245], v[196:199], v[66:69]
	v_mfma_f32_16x16x32_bf16 v[118:121], v[238:241], v[176:179], v[118:121]
	v_mfma_f32_16x16x32_bf16 v[114:117], v[246:249], v[176:179], v[114:117]
	v_mfma_f32_16x16x32_bf16 v[102:105], v[238:241], v[184:187], v[102:105]
	v_mfma_f32_16x16x32_bf16 v[98:101], v[246:249], v[184:187], v[98:101]
	v_mfma_f32_16x16x32_bf16 v[86:89], v[238:241], v[192:195], v[86:89]
	v_mfma_f32_16x16x32_bf16 v[82:85], v[246:249], v[192:195], v[82:85]
	v_mfma_f32_16x16x32_bf16 v[70:73], v[238:241], v[230:233], v[70:73]
	v_mfma_f32_16x16x32_bf16 v[66:69], v[246:249], v[230:233], v[66:69]
	s_setprio 0
	s_mov_b32 m0, s38
	v_lshl_add_u64 v[250:251], s[30:31], 0, v[130:131]
	s_barrier
	ds_read_b128 v[156:159], v151 offset:16384
	ds_read_b128 v[176:179], v151 offset:17408
	ds_read_b128 v[180:183], v151 offset:18432
	ds_read_b128 v[184:187], v151 offset:19456
	ds_read_b128 v[188:191], v151 offset:20480
	ds_read_b128 v[192:195], v151 offset:21504
	ds_read_b128 v[196:199], v151 offset:22528
	ds_read_b128 v[230:233], v151 offset:23552
	global_load_lds_dwordx4 v[250:251], off
	v_lshl_add_u64 v[252:253], s[30:31], 0, v[132:133]
	s_mov_b32 m0, s39
	s_nop 0
	global_load_lds_dwordx4 v[252:253], off
	s_barrier
	s_waitcnt lgkmcnt(0)
	s_setprio 1
	s_waitcnt lgkmcnt(0)
	v_mfma_f32_16x16x32_bf16 v[62:65], v[138:141], v[156:159], v[62:65]
	v_mfma_f32_16x16x32_bf16 v[58:61], v[146:149], v[156:159], v[58:61]
	v_mfma_f32_16x16x32_bf16 v[46:49], v[138:141], v[180:183], v[46:49]
	v_mfma_f32_16x16x32_bf16 v[42:45], v[146:149], v[180:183], v[42:45]
	v_mfma_f32_16x16x32_bf16 v[30:33], v[138:141], v[188:191], v[30:33]
	v_mfma_f32_16x16x32_bf16 v[26:29], v[146:149], v[188:191], v[26:29]
	v_mfma_f32_16x16x32_bf16 v[14:17], v[138:141], v[196:199], v[14:17]
	v_mfma_f32_16x16x32_bf16 v[10:13], v[146:149], v[196:199], v[10:13]
	v_mfma_f32_16x16x32_bf16 v[62:65], v[142:145], v[176:179], v[62:65]
	v_mfma_f32_16x16x32_bf16 v[58:61], v[152:155], v[176:179], v[58:61]
	v_mfma_f32_16x16x32_bf16 v[46:49], v[142:145], v[184:187], v[46:49]
	v_mfma_f32_16x16x32_bf16 v[42:45], v[152:155], v[184:187], v[42:45]
	v_mfma_f32_16x16x32_bf16 v[30:33], v[142:145], v[192:195], v[30:33]
	v_mfma_f32_16x16x32_bf16 v[26:29], v[152:155], v[192:195], v[26:29]
	v_mfma_f32_16x16x32_bf16 v[14:17], v[142:145], v[230:233], v[14:17]
	v_mfma_f32_16x16x32_bf16 v[10:13], v[152:155], v[230:233], v[10:13]
	s_setprio 0
	s_barrier
	s_add_u32 s48, s28, 0x40000
	s_addc_u32 s49, s29, 0
	s_add_i32 s50, s50, s37
	v_lshl_add_u64 v[138:139], s[48:49], 0, v[130:131]
	s_mov_b32 m0, s50
	s_nop 0
	global_load_lds_dwordx4 v[138:139], off
	v_lshl_add_u64 v[138:139], s[48:49], 0, v[132:133]
	s_add_i32 m0, s50, 0x2000
	s_nop 0
	global_load_lds_dwordx4 v[138:139], off
	s_waitcnt vmcnt(6)
	s_barrier
	s_setprio 1
	v_mfma_f32_16x16x32_bf16 v[54:57], v[234:237], v[156:159], v[54:57]
	v_mfma_f32_16x16x32_bf16 v[50:53], v[242:245], v[156:159], v[50:53]
	v_mfma_f32_16x16x32_bf16 v[38:41], v[234:237], v[180:183], v[38:41]
	v_mfma_f32_16x16x32_bf16 v[34:37], v[242:245], v[180:183], v[34:37]
	v_mfma_f32_16x16x32_bf16 v[22:25], v[234:237], v[188:191], v[22:25]
	v_mfma_f32_16x16x32_bf16 v[18:21], v[242:245], v[188:191], v[18:21]
	v_mfma_f32_16x16x32_bf16 v[6:9], v[234:237], v[196:199], v[6:9]
	v_mfma_f32_16x16x32_bf16 v[2:5], v[242:245], v[196:199], v[2:5]
	v_mfma_f32_16x16x32_bf16 v[54:57], v[238:241], v[176:179], v[54:57]
	v_mfma_f32_16x16x32_bf16 v[50:53], v[246:249], v[176:179], v[50:53]
	v_mfma_f32_16x16x32_bf16 v[38:41], v[238:241], v[184:187], v[38:41]
	v_mfma_f32_16x16x32_bf16 v[34:37], v[246:249], v[184:187], v[34:37]
	v_mfma_f32_16x16x32_bf16 v[22:25], v[238:241], v[192:195], v[22:25]
	v_mfma_f32_16x16x32_bf16 v[18:21], v[246:249], v[192:195], v[18:21]
	v_mfma_f32_16x16x32_bf16 v[6:9], v[238:241], v[230:233], v[6:9]
	v_mfma_f32_16x16x32_bf16 v[2:5], v[246:249], v[230:233], v[2:5]
	s_setprio 0
	s_add_i32 s48, 0, 0x18000
	v_add_u32_e32 v0, s48, v150
	s_barrier
	ds_read_b128 v[138:141], v0
	ds_read_b128 v[142:145], v0 offset:1024
	ds_read_b128 v[146:149], v0 offset:2048
	ds_read_b128 v[152:155], v0 offset:3072
	s_add_u32 s30, s30, 0x40000
	s_addc_u32 s31, s31, 0
	s_mov_b32 m0, s40
	v_lshl_add_u64 v[234:235], s[30:31], 0, v[130:131]
	ds_read_b128 v[156:159], v151 offset:32768
	ds_read_b128 v[176:179], v151 offset:33792
	ds_read_b128 v[180:183], v151 offset:34816
	ds_read_b128 v[184:187], v151 offset:35840
	ds_read_b128 v[188:191], v151 offset:36864
	ds_read_b128 v[192:195], v151 offset:37888
	ds_read_b128 v[196:199], v151 offset:38912
	ds_read_b128 v[230:233], v151 offset:39936
	global_load_lds_dwordx4 v[234:235], off
	v_lshl_add_u64 v[234:235], s[30:31], 0, v[132:133]
	s_mov_b32 m0, s41
	s_nop 0
	global_load_lds_dwordx4 v[234:235], off
	s_waitcnt lgkmcnt(8)
	s_barrier
	s_waitcnt lgkmcnt(0)
	s_setprio 1
	s_waitcnt lgkmcnt(0)
	v_mfma_f32_16x16x32_bf16 v[126:129], v[138:141], v[156:159], v[126:129]
	v_mfma_f32_16x16x32_bf16 v[122:125], v[146:149], v[156:159], v[122:125]
	v_mfma_f32_16x16x32_bf16 v[110:113], v[138:141], v[180:183], v[110:113]
	v_mfma_f32_16x16x32_bf16 v[106:109], v[146:149], v[180:183], v[106:109]
	v_mfma_f32_16x16x32_bf16 v[94:97], v[138:141], v[188:191], v[94:97]
	v_mfma_f32_16x16x32_bf16 v[90:93], v[146:149], v[188:191], v[90:93]
	v_mfma_f32_16x16x32_bf16 v[78:81], v[138:141], v[196:199], v[78:81]
	v_mfma_f32_16x16x32_bf16 v[74:77], v[146:149], v[196:199], v[74:77]
	v_mfma_f32_16x16x32_bf16 v[126:129], v[142:145], v[176:179], v[126:129]
	v_mfma_f32_16x16x32_bf16 v[122:125], v[152:155], v[176:179], v[122:125]
	v_mfma_f32_16x16x32_bf16 v[110:113], v[142:145], v[184:187], v[110:113]
	v_mfma_f32_16x16x32_bf16 v[106:109], v[152:155], v[184:187], v[106:109]
	v_mfma_f32_16x16x32_bf16 v[94:97], v[142:145], v[192:195], v[94:97]
	v_mfma_f32_16x16x32_bf16 v[90:93], v[152:155], v[192:195], v[90:93]
	v_mfma_f32_16x16x32_bf16 v[78:81], v[142:145], v[230:233], v[78:81]
	v_mfma_f32_16x16x32_bf16 v[74:77], v[152:155], v[230:233], v[74:77]
	s_setprio 0
	s_barrier
	s_add_i32 s30, 0, 0x1c000
	s_add_i32 s31, s48, s37
	v_add_u32_e32 v0, s30, v150
	v_lshl_add_u64 v[160:161], v[160:161], 0, s[92:93]
	s_mov_b32 m0, s31
	ds_read_b128 v[234:237], v0
	ds_read_b128 v[238:241], v0 offset:1024
	ds_read_b128 v[242:245], v0 offset:2048
	ds_read_b128 v[246:249], v0 offset:3072
	global_load_lds_dwordx4 v[160:161], off
	v_lshl_add_u64 v[160:161], v[200:201], 0, s[92:93]
	s_add_i32 m0, s31, 0x2000
	s_nop 0
	global_load_lds_dwordx4 v[160:161], off
	s_barrier
	s_waitcnt lgkmcnt(0)
	s_setprio 1
	s_waitcnt lgkmcnt(0)
	v_mfma_f32_16x16x32_bf16 v[118:121], v[234:237], v[156:159], v[118:121]
	v_mfma_f32_16x16x32_bf16 v[114:117], v[242:245], v[156:159], v[114:117]
	v_mfma_f32_16x16x32_bf16 v[102:105], v[234:237], v[180:183], v[102:105]
	v_mfma_f32_16x16x32_bf16 v[98:101], v[242:245], v[180:183], v[98:101]
	v_mfma_f32_16x16x32_bf16 v[86:89], v[234:237], v[188:191], v[86:89]
	v_mfma_f32_16x16x32_bf16 v[82:85], v[242:245], v[188:191], v[82:85]
	v_mfma_f32_16x16x32_bf16 v[70:73], v[234:237], v[196:199], v[70:73]
	v_mfma_f32_16x16x32_bf16 v[66:69], v[242:245], v[196:199], v[66:69]
	v_mfma_f32_16x16x32_bf16 v[118:121], v[238:241], v[176:179], v[118:121]
	v_mfma_f32_16x16x32_bf16 v[114:117], v[246:249], v[176:179], v[114:117]
	v_mfma_f32_16x16x32_bf16 v[102:105], v[238:241], v[184:187], v[102:105]
	v_mfma_f32_16x16x32_bf16 v[98:101], v[246:249], v[184:187], v[98:101]
	v_mfma_f32_16x16x32_bf16 v[86:89], v[238:241], v[192:195], v[86:89]
	v_mfma_f32_16x16x32_bf16 v[82:85], v[246:249], v[192:195], v[82:85]
	v_mfma_f32_16x16x32_bf16 v[70:73], v[238:241], v[230:233], v[70:73]
	v_mfma_f32_16x16x32_bf16 v[66:69], v[246:249], v[230:233], v[66:69]
	s_setprio 0
	s_mov_b32 m0, s42
	v_lshl_add_u64 v[160:161], v[250:251], 0, s[92:93]
	s_barrier
	ds_read_b128 v[156:159], v151 offset:49152
	ds_read_b128 v[176:179], v151 offset:50176
	ds_read_b128 v[180:183], v151 offset:51200
	ds_read_b128 v[184:187], v151 offset:52224
	ds_read_b128 v[188:191], v151 offset:53248
	ds_read_b128 v[192:195], v151 offset:54272
	ds_read_b128 v[196:199], v151 offset:55296
	ds_read_b128 v[230:233], v151 offset:56320
	global_load_lds_dwordx4 v[160:161], off
	v_lshl_add_u64 v[160:161], v[252:253], 0, s[92:93]
	s_mov_b32 m0, s43
	s_nop 0
	global_load_lds_dwordx4 v[160:161], off
	s_barrier
	s_waitcnt lgkmcnt(0)
	s_setprio 1
	s_waitcnt lgkmcnt(0)
	v_mfma_f32_16x16x32_bf16 v[62:65], v[138:141], v[156:159], v[62:65]
	v_mfma_f32_16x16x32_bf16 v[58:61], v[146:149], v[156:159], v[58:61]
	v_mfma_f32_16x16x32_bf16 v[46:49], v[138:141], v[180:183], v[46:49]
	v_mfma_f32_16x16x32_bf16 v[42:45], v[146:149], v[180:183], v[42:45]
	v_mfma_f32_16x16x32_bf16 v[30:33], v[138:141], v[188:191], v[30:33]
	v_mfma_f32_16x16x32_bf16 v[26:29], v[146:149], v[188:191], v[26:29]
	v_mfma_f32_16x16x32_bf16 v[14:17], v[138:141], v[196:199], v[14:17]
	v_mfma_f32_16x16x32_bf16 v[10:13], v[146:149], v[196:199], v[10:13]
	v_mfma_f32_16x16x32_bf16 v[62:65], v[142:145], v[176:179], v[62:65]
	v_mfma_f32_16x16x32_bf16 v[58:61], v[152:155], v[176:179], v[58:61]
	v_mfma_f32_16x16x32_bf16 v[46:49], v[142:145], v[184:187], v[46:49]
	v_mfma_f32_16x16x32_bf16 v[42:45], v[152:155], v[184:187], v[42:45]
	v_mfma_f32_16x16x32_bf16 v[30:33], v[142:145], v[192:195], v[30:33]
	v_mfma_f32_16x16x32_bf16 v[26:29], v[152:155], v[192:195], v[26:29]
	v_mfma_f32_16x16x32_bf16 v[14:17], v[142:145], v[230:233], v[14:17]
	v_mfma_f32_16x16x32_bf16 v[10:13], v[152:155], v[230:233], v[10:13]
	s_setprio 0
	s_barrier
	s_add_u32 s28, s28, 0x40080
	s_addc_u32 s29, s29, 0
	s_add_i32 s30, s30, s37
	v_lshl_add_u64 v[138:139], s[28:29], 0, v[130:131]
	s_mov_b32 m0, s30
	s_nop 0
	global_load_lds_dwordx4 v[138:139], off
	v_lshl_add_u64 v[138:139], s[28:29], 0, v[132:133]
	s_add_i32 m0, s30, 0x2000
	s_nop 0
	global_load_lds_dwordx4 v[138:139], off
	s_waitcnt vmcnt(6)
	s_barrier
	s_setprio 1
	v_mfma_f32_16x16x32_bf16 v[54:57], v[234:237], v[156:159], v[54:57]
	v_mfma_f32_16x16x32_bf16 v[50:53], v[242:245], v[156:159], v[50:53]
	v_mfma_f32_16x16x32_bf16 v[38:41], v[234:237], v[180:183], v[38:41]
	v_mfma_f32_16x16x32_bf16 v[34:37], v[242:245], v[180:183], v[34:37]
	v_mfma_f32_16x16x32_bf16 v[22:25], v[234:237], v[188:191], v[22:25]
	v_mfma_f32_16x16x32_bf16 v[18:21], v[242:245], v[188:191], v[18:21]
	v_mfma_f32_16x16x32_bf16 v[6:9], v[234:237], v[196:199], v[6:9]
	v_mfma_f32_16x16x32_bf16 v[2:5], v[242:245], v[196:199], v[2:5]
	v_mfma_f32_16x16x32_bf16 v[54:57], v[238:241], v[176:179], v[54:57]
	v_mfma_f32_16x16x32_bf16 v[50:53], v[246:249], v[176:179], v[50:53]
	v_mfma_f32_16x16x32_bf16 v[38:41], v[238:241], v[184:187], v[38:41]
	v_mfma_f32_16x16x32_bf16 v[34:37], v[246:249], v[184:187], v[34:37]
	v_mfma_f32_16x16x32_bf16 v[22:25], v[238:241], v[192:195], v[22:25]
	v_mfma_f32_16x16x32_bf16 v[18:21], v[246:249], v[192:195], v[18:21]
	v_mfma_f32_16x16x32_bf16 v[6:9], v[238:241], v[230:233], v[6:9]
	v_mfma_f32_16x16x32_bf16 v[2:5], v[246:249], v[230:233], v[2:5]
	s_setprio 0
	s_add_i32 s47, s47, 2
	s_add_u32 s34, s34, 0x100
	s_addc_u32 s35, s35, 0
	s_add_u32 s26, s26, 0x100
	s_addc_u32 s27, s27, 0
	s_cmp_gt_u32 s47, 13
	s_barrier
	s_cbranch_scc0 .LBB0_918
	v_mov_b32_e32 v0, v163
	s_movk_i32 s7, 0xffc0
	v_and_b32_e32 v138, 0xc0, v0
	v_and_b32_e32 v139, 15, v0
	v_ashrrev_i32_e32 v140, 2, v0
	v_lshl_or_b32 v152, s8, 8, v138
	v_lshrrev_b32_e32 v0, 1, v0
	v_and_or_b32 v138, v0, 24, v152
	v_add_u32_e32 v178, 0xfffff880, v138
	v_cmp_gt_u32_e32 vcc, 16, v178
	s_and_saveexec_b64 s[98:99], vcc
	s_cbranch_execz .Lip_nobias
	v_mov_b32_e32 v179, 0
	v_lshlrev_b64 v[178:179], 2, v[178:179]
	v_lshl_add_u64 v[186:187], s[16:17], 0, v[178:179]
	global_load_dwordx4 v[178:181], v[186:187], off
	global_load_dwordx4 v[182:185], v[186:187], off offset:16
	s_waitcnt vmcnt(0)
.Lip_nobias:
	s_or_b64 exec, exec, s[98:99]
	v_and_or_b32 v0, v140, s7, v139
	v_lshl_add_u32 v140, s6, 8, v0
	v_ashrrev_i32_e32 v141, 31, v140
	s_movk_i32 s6, 0x39f
	v_lshlrev_b64 v[144:145], 10, v[140:141]
	v_lshlrev_b64 v[142:143], 4, v[140:141]
	v_lshlrev_b64 v[146:147], 11, v[140:141]
	v_cmp_lt_i32_e64 s[6:7], s6, v138
	s_and_saveexec_b64 s[8:9], s[6:7]
	s_xor_b64 s[8:9], exec, s[8:9]
	s_cbranch_execz .LBB0_931
	s_movk_i32 s19, 0x79f
	v_cmp_lt_u32_e32 vcc, s19, v152
	s_and_saveexec_b64 s[26:27], vcc
	s_xor_b64 s[26:27], exec, s[26:27]
	s_cbranch_execz .LBB0_928
	s_movk_i32 s19, 0x7af
	v_cmp_lt_u32_e32 vcc, s19, v138
	s_and_saveexec_b64 s[28:29], vcc
	s_xor_b64 s[28:29], exec, s[28:29]
	s_cbranch_execz .LBB0_925
	s_movk_i32 s19, 0x9b0
	v_cmp_gt_u32_e32 vcc, s19, v138
	s_and_saveexec_b64 s[30:31], vcc
	s_cbranch_execz .LBB0_924
	v_lshl_add_u64 v[148:149], s[10:11], 0, v[144:145]
	v_mov_b32_e32 v139, v1
	v_lshl_add_u64 v[148:149], v[138:139], 1, v[148:149]
	v_cvt_pk_bf16_f32 v154, v126, v127
	v_cvt_pk_bf16_f32 v155, v128, v129
	v_cvt_pk_bf16_f32 v156, v122, v123
	v_cvt_pk_bf16_f32 v157, v124, v125
	global_store_dwordx4 v[148:149], v[154:157], off offset:-3936

.LBB0_939:
	s_andn2_saveexec_b64 s[8:9], s[30:31]
	s_cbranch_execz .LBB0_941
	v_add_u32_e32 v0, 0xfffff880, v138
	v_lshlrev_b64 v[128:129], 2, v[0:1]
	v_lshl_add_u64 v[142:143], v[142:143], 2, s[14:15]
	v_lshl_add_u64 v[128:129], v[142:143], 0, v[128:129]
	v_pk_add_f32 v[126:127], v[120:121], v[180:181]
	v_pk_add_f32 v[124:125], v[118:119], v[178:179]
	v_pk_add_f32 v[146:147], v[116:117], v[184:185]
	v_pk_add_f32 v[144:145], v[114:115], v[182:183]
	global_store_dwordx4 v[128:129], v[124:127], off
	global_store_dwordx4 v[128:129], v[144:147], off offset:16

.LBB0_1064:
	s_andn2_saveexec_b64 s[8:9], s[30:31]
	s_cbranch_execz .LBB0_1066
	v_add_u32_e32 v0, 0xfffff880, v138
	v_lshlrev_b64 v[116:117], 2, v[0:1]
	v_lshl_add_u64 v[114:115], v[114:115], 2, s[14:15]
	v_lshl_add_u64 v[114:115], v[114:115], 0, v[116:117]
	v_pk_add_f32 v[108:109], v[104:105], v[180:181]
	v_pk_add_f32 v[106:107], v[102:103], v[178:179]
	v_pk_add_f32 v[112:113], v[100:101], v[184:185]
	v_pk_add_f32 v[110:111], v[98:99], v[182:183]
	global_store_dwordx4 v[114:115], v[106:109], off
	global_store_dwordx4 v[114:115], v[110:113], off offset:16

.LBB0_1076:
	s_andn2_saveexec_b64 s[8:9], s[30:31]
	s_cbranch_execz .LBB0_1078
	v_add_u32_e32 v0, 0xfffff880, v138
	v_lshlrev_b64 v[100:101], 2, v[0:1]
	v_lshl_add_u64 v[98:99], v[98:99], 2, s[14:15]
	v_lshl_add_u64 v[98:99], v[98:99], 0, v[100:101]
	v_pk_add_f32 v[92:93], v[88:89], v[180:181]
	v_pk_add_f32 v[90:91], v[86:87], v[178:179]
	v_pk_add_f32 v[96:97], v[84:85], v[184:185]
	v_pk_add_f32 v[94:95], v[82:83], v[182:183]
	global_store_dwordx4 v[98:99], v[90:93], off
	global_store_dwordx4 v[98:99], v[94:97], off offset:16

.LBB0_1088:
	s_andn2_saveexec_b64 s[8:9], s[30:31]
	s_cbranch_execz .LBB0_1090
	v_add_u32_e32 v0, 0xfffff880, v138
	v_lshlrev_b64 v[84:85], 2, v[0:1]
	v_lshl_add_u64 v[82:83], v[82:83], 2, s[14:15]
	v_lshl_add_u64 v[82:83], v[82:83], 0, v[84:85]
	v_pk_add_f32 v[76:77], v[72:73], v[180:181]
	v_pk_add_f32 v[74:75], v[70:71], v[178:179]
	v_pk_add_f32 v[80:81], v[68:69], v[184:185]
	v_pk_add_f32 v[78:79], v[66:67], v[182:183]
	global_store_dwordx4 v[82:83], v[74:77], off
	global_store_dwordx4 v[82:83], v[78:81], off offset:16

.LBB0_1100:
	s_andn2_saveexec_b64 s[8:9], s[30:31]
	s_cbranch_execz .LBB0_1102
	v_add_u32_e32 v0, 0xfffff880, v138
	v_lshlrev_b64 v[68:69], 2, v[0:1]
	v_lshl_add_u64 v[66:67], v[66:67], 2, s[14:15]
	v_lshl_add_u64 v[66:67], v[66:67], 0, v[68:69]
	v_pk_add_f32 v[60:61], v[56:57], v[180:181]
	v_pk_add_f32 v[58:59], v[54:55], v[178:179]
	v_pk_add_f32 v[64:65], v[52:53], v[184:185]
	v_pk_add_f32 v[62:63], v[50:51], v[182:183]
	global_store_dwordx4 v[66:67], v[58:61], off
	global_store_dwordx4 v[66:67], v[62:65], off offset:16

.LBB0_1112:
	s_andn2_saveexec_b64 s[8:9], s[30:31]
	s_cbranch_execz .LBB0_1114
	v_add_u32_e32 v0, 0xfffff880, v138
	v_lshlrev_b64 v[52:53], 2, v[0:1]
	v_lshl_add_u64 v[50:51], v[50:51], 2, s[14:15]
	v_lshl_add_u64 v[50:51], v[50:51], 0, v[52:53]
	v_pk_add_f32 v[44:45], v[40:41], v[180:181]
	v_pk_add_f32 v[42:43], v[38:39], v[178:179]
	v_pk_add_f32 v[48:49], v[36:37], v[184:185]
	v_pk_add_f32 v[46:47], v[34:35], v[182:183]
	global_store_dwordx4 v[50:51], v[42:45], off
	global_store_dwordx4 v[50:51], v[46:49], off offset:16

.LBB0_1124:
	s_andn2_saveexec_b64 s[8:9], s[30:31]
	s_cbranch_execz .LBB0_1126
	v_add_u32_e32 v0, 0xfffff880, v138
	v_lshlrev_b64 v[36:37], 2, v[0:1]
	v_lshl_add_u64 v[34:35], v[34:35], 2, s[14:15]
	v_lshl_add_u64 v[34:35], v[34:35], 0, v[36:37]
	v_pk_add_f32 v[28:29], v[24:25], v[180:181]
	v_pk_add_f32 v[26:27], v[22:23], v[178:179]
	v_pk_add_f32 v[32:33], v[20:21], v[184:185]
	v_pk_add_f32 v[30:31], v[18:19], v[182:183]
	global_store_dwordx4 v[34:35], v[26:29], off
	global_store_dwordx4 v[34:35], v[30:33], off offset:16

.LBB0_1136:
	s_andn2_saveexec_b64 s[26:27], s[26:27]
	s_cbranch_execz .LBB0_1138
	v_add_u32_e32 v0, 0xfffff880, v138
	v_lshlrev_b64 v[20:21], 2, v[0:1]
	v_lshl_add_u64 v[18:19], v[18:19], 2, s[14:15]
	v_lshl_add_u64 v[18:19], v[18:19], 0, v[20:21]
	v_pk_add_f32 v[12:13], v[8:9], v[180:181]
	v_pk_add_f32 v[10:11], v[6:7], v[178:179]
	v_pk_add_f32 v[16:17], v[4:5], v[184:185]
	v_pk_add_f32 v[14:15], v[2:3], v[182:183]
	global_store_dwordx4 v[18:19], v[10:13], off
	global_store_dwordx4 v[18:19], v[14:17], off offset:16
